# attention (P3): one static s_setprio 1 for waves 4-7 at attention entry, reset at phase end; on top of v066
# speedup vs baseline: 1.0039x; 1.0039x over previous
; __global__ void __launch_bounds__(NWAVES * 64, 2) mk_fwd(Args args) {
;     ...
;     if (IN(3)) {
;         typedef fox::Body<LDP, HW> FB;
;         char* albs = (char*)lds_raw + RING_OFF;
;         if (bx < BATCH * NH) gdn_scan8((const unsigned char*)out, UF, EGp, OA, P, gdn_norm_w, lds + RING_OFF, bx);
.LBB0_553:
	v_readlane_b32 s32, v254, 0
	s_nop 3
	s_cmp_ge_u32 s32, 4
	s_cbranch_scc0 .Lfox_prio_done
	s_setprio 1

; __device__ __forceinline__ unsigned xb_ld(unsigned* p)              { return __hip_atomic_load(p, __ATOMIC_RELAXED, __HIP_MEMORY_SCOPE_AGENT); }
; __device__ __forceinline__ unsigned xb_add(unsigned* p, unsigned v) { return __hip_atomic_fetch_add(p, v, __ATOMIC_RELAXED, __HIP_MEMORY_SCOPE_AGENT); }
; __device__ __forceinline__ void xcd_barrier_complete(unsigned* bar, unsigned x, unsigned& nloc, unsigned& nx) {
;     const unsigned G = gridDim.x * gridDim.y * gridDim.z;
;     unsigned sum, cnt, mine, sp = 0u;
;     for (;;) {
;         sum = 0u; cnt = 0u; mine = 0u;
; #pragma unroll
;         for (unsigned j = 0; j < 16; ++j) { const unsigned c = xb_ld(&bar[XB_XCNT(j)]); sum += c; cnt += (c > 0u) ? 1u : 0u; mine = (j == x) ? c : mine; }
; __device__ __forceinline__ void xcd_barrier(const XcdBarrier& b) {
;     asm volatile("s_waitcnt vmcnt(0)" ::: "memory");
;     __syncthreads();
;     if (threadIdx.x == 0) {
;         unsigned* bar = b.bar;
;         __builtin_amdgcn_s_waitcnt(0);
;         unsigned nloc = b.st[0], nx = b.st[1];
;         if (nloc == 0u) { xcd_barrier_complete(bar, b.x, nloc, nx); b.st[0] = nloc; b.st[1] = nx; }
;         const unsigned old = xb_add(&bar[XB_XSUB(b.x)], 1u);
;         const unsigned gen = old / nloc;
;         if (old + 1u == (gen + 1u) * nloc) {
.LBB0_789:
	s_setprio 0
	s_cmp_gt_i32 s67, 4
	s_cselect_b64 s[0:1], -1, 0
	s_and_b64 s[2:3], s[2:3], s[0:1]
	v_readlane_b32 s16, v254, 27
	v_readlane_b32 s18, v254, 25
	v_readlane_b32 s20, v254, 23
	s_andn2_b64 vcc, exec, s[2:3]
	v_readlane_b32 s17, v254, 28
	v_readlane_b32 s19, v254, 26
	v_readlane_b32 s21, v254, 24
	s_cbranch_vccnz .LBB0_839
	s_waitcnt vmcnt(0)
	v_cmp_eq_u32_e32 vcc, 0, v0
	s_waitcnt vmcnt(0)
	s_barrier
	s_and_saveexec_b64 s[2:3], vcc
	s_cbranch_execz .LBB0_838
	v_readlane_b32 s4, v254, 6
	s_waitcnt vmcnt(0) expcnt(0) lgkmcnt(0)
	s_nop 0
	v_mov_b32_e32 v1, s4
	ds_read_b32 v3, v1
	ds_read_b32 v1, v1 offset:4
	s_waitcnt lgkmcnt(1)
	v_cmp_ne_u32_e32 vcc, 0, v3
	s_cbranch_vccnz .LBB0_806
	v_readlane_b32 s4, v254, 1
	v_readlane_b32 s5, v254, 2
	s_load_dwordx2 s[8:9], s[4:5], 0x4
	s_add_u32 s4, s64, 0x4200
	s_addc_u32 s5, s65, 0
	s_add_u32 s6, s64, 0x4400
	s_addc_u32 s7, s65, 0
	s_waitcnt lgkmcnt(0)
	s_mul_i32 s33, s8, s72
	s_add_u32 s8, s64, 0x4500
	s_mul_i32 s33, s33, s9
	s_addc_u32 s9, s65, 0
	s_add_u32 s10, s64, 0x4600
	s_addc_u32 s11, s65, 0
	s_add_u32 s12, s64, 0x4700
	s_addc_u32 s13, s65, 0
	s_add_u32 s14, s64, 0x4800
	s_addc_u32 s15, s65, 0
	s_add_u32 s24, s64, 0x4900
	s_addc_u32 s25, s65, 0
	s_add_u32 s26, s64, 0x4a00
	s_addc_u32 s27, s65, 0
	s_add_u32 s28, s64, 0x4b00
	s_addc_u32 s29, s65, 0
	s_add_u32 s30, s64, 0x4c00
	s_addc_u32 s31, s65, 0
	s_add_u32 s34, s64, 0x4d00
	s_addc_u32 s35, s65, 0
	s_add_u32 s36, s64, 0x4e00
	s_addc_u32 s37, s65, 0
	s_add_u32 s38, s64, 0x4f00
	s_addc_u32 s39, s65, 0
	s_add_u32 s40, s64, 0x5000
	s_addc_u32 s41, s65, 0
	s_add_u32 s42, s64, 0x5100
	s_addc_u32 s43, s65, 0
	s_add_u32 s44, s64, 0x5200
	s_addc_u32 s45, s65, 0
	s_add_u32 s46, s64, 0x5300
	s_addc_u32 s47, s65, 0
	s_mov_b32 s56, 1
	v_mov_b32_e32 v17, 0
	s_branch .LBB0_794
